# differential-attention fast loop without the static priority raise
# speedup vs baseline: 1.0140x; 1.0021x over previous
.LfA_enter:
	s_mov_b32 s30, s6
	v_and_b32_e32 v246, 15, v184
	v_lshlrev_b32_e32 v246, 4, v246
	v_lshl_add_u32 v246, v196, 1, v246
	s_lshl_b64 s[8:9], s[12:13], 13
	s_add_u32 s98, s10, s28
	s_addc_u32 s99, s11, 0
	s_add_u32 s98, s98, s8
	s_addc_u32 s99, s99, s9
	s_mov_b32 s101, 0
	v_add_u32_e32 v1, s27, v227
	v_add_u32_e32 v14, v1, v207
	v_add_u32_e32 v15, v1, v224
	v_add_u32_e32 v235, v1, v225
	v_add_u32_e32 v244, v1, v226
	v_add_u32_e32 v1, s30, v227
	v_add_u32_e32 v245, v1, v207
	ds_read_b128 v[2:5], v245 offset:8192
	v_add_u32_e32 v245, v1, v224
	ds_read_b128 v[6:9], v245 offset:8192
	v_add_u32_e32 v245, v1, v225
	ds_read_b128 v[10:13], v245 offset:8192
	v_add_u32_e32 v245, v1, v226
	ds_read_b128 v[152:155], v245 offset:8192
	v_add_u32_e32 v245, s25, v233
	ds_read_b64_tr_b16 v[156:157], v245 offset:10240
	ds_read_b64_tr_b16 v[158:159], v245 offset:12800
	ds_read_b64_tr_b16 v[160:161], v245 offset:10304
	ds_read_b64_tr_b16 v[162:163], v245 offset:12864
	ds_read_b64_tr_b16 v[164:165], v245 offset:10368
	ds_read_b64_tr_b16 v[166:167], v245 offset:12928
	ds_read_b64_tr_b16 v[168:169], v245 offset:10432
	ds_read_b64_tr_b16 v[170:171], v245 offset:12992
	s_waitcnt lgkmcnt(0)
.LfA_iter:
	s_add_u32 s8, s98, 0x40000
	s_addc_u32 s9, s99, 0
	s_sub_u32 s18, s98, 0x80000
	s_subb_u32 s19, s99, 0
	s_sub_u32 s20, s98, 0x40000
	s_subb_u32 s21, s99, 0
	v_add_u32_e32 v1, s30, v233
	s_waitcnt lgkmcnt(2)
	v_mfma_f32_32x32x16_bf16 v[80:95], v[2:5], v[112:115], 0
	ds_read_b64_tr_b16 v[2:3], v245 offset:15360
	ds_read_b64_tr_b16 v[4:5], v245 offset:17920
	v_exp_f32_e32 v96, v96
	v_exp_f32_e32 v97, v97
	v_add_u32_e32 v14, s101, v14
	v_add_u32_e32 v15, s101, v15
	v_mfma_f32_32x32x16_bf16 v[64:79], v[156:159], v[148:151], v[64:79]
	ds_read_b64_tr_b16 v[156:157], v1 offset:0
	ds_read_b64_tr_b16 v[158:159], v1 offset:2560
	v_exp_f32_e32 v98, v98
	v_exp_f32_e32 v99, v99
	v_add_f32_e32 v228, v228, v96
	v_add_u32_e32 v235, s101, v235
	v_mfma_f32_32x32x16_bf16 v[80:95], v[6:9], v[116:119], v[80:95]
	ds_read_b64_tr_b16 v[6:7], v245 offset:15424
	ds_read_b64_tr_b16 v[8:9], v245 offset:17984
	v_exp_f32_e32 v100, v100
	v_exp_f32_e32 v101, v101
	v_add_f32_e32 v228, v228, v97
	v_add_u32_e32 v244, s101, v244
	global_load_dwordx4 v[128:131], v246, s[98:99] offset:1024
	global_load_dwordx4 v[132:135], v246, s[8:9] offset:1024
	v_mfma_f32_32x32x16_bf16 v[48:63], v[160:163], v[148:151], v[48:63]
	ds_read_b64_tr_b16 v[160:161], v1 offset:64
	ds_read_b64_tr_b16 v[162:163], v1 offset:2624
	v_exp_f32_e32 v102, v102
	v_exp_f32_e32 v103, v103
	v_add_f32_e32 v228, v228, v98
	v_add_f32_e32 v228, v228, v99
	s_waitcnt lgkmcnt(8)
	v_mfma_f32_32x32x16_bf16 v[80:95], v[10:13], v[120:123], v[80:95]
	ds_read_b64_tr_b16 v[10:11], v245 offset:15488
	ds_read_b64_tr_b16 v[12:13], v245 offset:18048
	v_exp_f32_e32 v104, v104
	v_exp_f32_e32 v105, v105
	v_add_f32_e32 v228, v228, v100
	v_add_f32_e32 v228, v228, v101
	v_mfma_f32_32x32x16_bf16 v[16:31], v[164:167], v[148:151], v[16:31]
	ds_read_b64_tr_b16 v[164:165], v1 offset:128
	ds_read_b64_tr_b16 v[166:167], v1 offset:2688
	v_exp_f32_e32 v106, v106
	v_exp_f32_e32 v107, v107
	v_add_f32_e32 v228, v228, v102
	v_add_f32_e32 v228, v228, v103
	global_load_dwordx4 v[136:139], v246, s[18:19] offset:2048
	global_load_dwordx4 v[140:143], v246, s[20:21] offset:2048
	s_add_u32 s98, s98, 0x80000
	s_addc_u32 s99, s99, 0
	v_mfma_f32_32x32x16_bf16 v[80:95], v[152:155], v[124:127], v[80:95]
	ds_read_b64_tr_b16 v[152:153], v245 offset:15552
	ds_read_b64_tr_b16 v[154:155], v245 offset:18112
	v_exp_f32_e32 v108, v108
	v_exp_f32_e32 v109, v109
	v_add_f32_e32 v228, v228, v104
	v_add_f32_e32 v228, v228, v105
	v_mfma_f32_32x32x16_bf16 v[32:47], v[168:171], v[148:151], v[32:47]
	ds_read_b64_tr_b16 v[168:169], v1 offset:192
	ds_read_b64_tr_b16 v[170:171], v1 offset:2752
	v_exp_f32_e32 v110, v110
	v_exp_f32_e32 v111, v111
	v_add_f32_e32 v228, v228, v106
	v_add_f32_e32 v228, v228, v107
	s_waitcnt lgkmcnt(10)
	v_mfma_f32_32x32x16_bf16 v[64:79], v[2:5], v[144:147], v[64:79]
	ds_read_b128 v[236:239], v14
	v_cvt_pk_bf16_f32 v148, v96, v97
	v_cvt_pk_bf16_f32 v149, v98, v99
	v_cvt_pk_bf16_f32 v150, v100, v101
	v_cvt_pk_bf16_f32 v151, v102, v103
	v_add_f32_e32 v228, v228, v108
	v_mfma_f32_32x32x16_bf16 v[48:63], v[6:9], v[144:147], v[48:63]
	ds_read_b128 v[240:243], v15
	v_add_f32_e32 v228, v228, v109
	v_add_f32_e32 v228, v228, v110
	v_add_f32_e32 v228, v228, v111
	s_waitcnt lgkmcnt(4)
	v_mfma_f32_32x32x16_bf16 v[16:31], v[10:13], v[144:147], v[16:31]
	ds_read_b128 v[248:251], v235
	v_mov_b32_e32 v245, v1
	v_mfma_f32_32x32x16_bf16 v[32:47], v[152:155], v[144:147], v[32:47]
	ds_read_b128 v[252:255], v244
	v_cvt_pk_bf16_f32 v144, v104, v105
	v_cvt_pk_bf16_f32 v145, v106, v107
	v_cvt_pk_bf16_f32 v146, v108, v109
	v_cvt_pk_bf16_f32 v147, v110, v111
	s_waitcnt lgkmcnt(2)
	v_mfma_f32_32x32x16_bf16 v[96:111], v[236:239], v[112:115], 0
	ds_read_b64_tr_b16 v[236:237], v245 offset:5120
	ds_read_b64_tr_b16 v[238:239], v245 offset:7680
	v_exp_f32_e32 v80, v80
	v_exp_f32_e32 v81, v81
	v_mfma_f32_32x32x16_bf16 v[64:79], v[156:159], v[148:151], v[64:79]
	ds_read_b64_tr_b16 v[156:157], v245 offset:10240
	ds_read_b64_tr_b16 v[158:159], v245 offset:12800
	v_exp_f32_e32 v82, v82
	v_exp_f32_e32 v83, v83
	v_add_f32_e32 v228, v228, v80
	v_mfma_f32_32x32x16_bf16 v[96:111], v[240:243], v[116:119], v[96:111]
	ds_read_b64_tr_b16 v[240:241], v245 offset:5184
	ds_read_b64_tr_b16 v[242:243], v245 offset:7744
	v_exp_f32_e32 v84, v84
	v_exp_f32_e32 v85, v85
	v_add_f32_e32 v228, v228, v81
	v_mfma_f32_32x32x16_bf16 v[48:63], v[160:163], v[148:151], v[48:63]
	ds_read_b64_tr_b16 v[160:161], v245 offset:10304
	ds_read_b64_tr_b16 v[162:163], v245 offset:12864
	v_exp_f32_e32 v86, v86
	v_exp_f32_e32 v87, v87
	v_add_f32_e32 v228, v228, v82
	v_add_f32_e32 v228, v228, v83
	s_waitcnt lgkmcnt(8)
	v_mfma_f32_32x32x16_bf16 v[96:111], v[248:251], v[120:123], v[96:111]
	ds_read_b64_tr_b16 v[248:249], v245 offset:5248
	ds_read_b64_tr_b16 v[250:251], v245 offset:7808
	v_exp_f32_e32 v88, v88
	v_exp_f32_e32 v89, v89
	v_add_f32_e32 v228, v228, v84
	v_add_f32_e32 v228, v228, v85
	v_mfma_f32_32x32x16_bf16 v[16:31], v[164:167], v[148:151], v[16:31]
	ds_read_b64_tr_b16 v[164:165], v245 offset:10368
	ds_read_b64_tr_b16 v[166:167], v245 offset:12928
	v_exp_f32_e32 v90, v90
	v_exp_f32_e32 v91, v91
	v_add_f32_e32 v228, v228, v86
	v_add_f32_e32 v228, v228, v87
	v_mfma_f32_32x32x16_bf16 v[96:111], v[252:255], v[124:127], v[96:111]
	ds_read_b64_tr_b16 v[252:253], v245 offset:5312
	ds_read_b64_tr_b16 v[254:255], v245 offset:7872
	v_exp_f32_e32 v92, v92
	v_exp_f32_e32 v93, v93
	v_add_f32_e32 v228, v228, v88
	v_add_f32_e32 v228, v228, v89
	v_mfma_f32_32x32x16_bf16 v[32:47], v[168:171], v[148:151], v[32:47]
	ds_read_b64_tr_b16 v[168:169], v245 offset:10432
	ds_read_b64_tr_b16 v[170:171], v245 offset:12992
	v_exp_f32_e32 v94, v94
	v_exp_f32_e32 v95, v95
	v_add_f32_e32 v228, v228, v90
	v_add_f32_e32 v228, v228, v91
	s_waitcnt lgkmcnt(10)
	v_mfma_f32_32x32x16_bf16 v[64:79], v[236:239], v[144:147], v[64:79]
	s_waitcnt vmcnt(0)
	v_add_u32_e32 v1, s25, v206
	ds_write_b128 v1, v[128:131]
	ds_write_b128 v1, v[132:135] offset:8192
	v_cvt_pk_bf16_f32 v148, v80, v81
	v_cvt_pk_bf16_f32 v149, v82, v83
	v_cvt_pk_bf16_f32 v150, v84, v85
	v_cvt_pk_bf16_f32 v151, v86, v87
	v_add_f32_e32 v228, v228, v92
	v_mfma_f32_32x32x16_bf16 v[48:63], v[240:243], v[144:147], v[48:63]
	v_add_u32_e32 v1, s27, v205
	ds_write_b128 v1, v[136:139] offset:16384
	ds_write_b128 v1, v[140:143] offset:26624
	v_add_f32_e32 v228, v228, v93
	v_add_f32_e32 v228, v228, v94
	v_add_f32_e32 v228, v228, v95
	s_waitcnt lgkmcnt(6)
	v_mfma_f32_32x32x16_bf16 v[16:31], v[248:251], v[144:147], v[16:31]
	ds_read_b128 v[2:5], v14 offset:8192
	ds_read_b128 v[6:9], v15 offset:8192
	v_mfma_f32_32x32x16_bf16 v[32:47], v[252:255], v[144:147], v[32:47]
	ds_read_b128 v[10:13], v235 offset:8192
	ds_read_b128 v[152:155], v244 offset:8192
	v_cvt_pk_bf16_f32 v144, v88, v89
	v_cvt_pk_bf16_f32 v145, v90, v91
	v_cvt_pk_bf16_f32 v146, v92, v93
	v_cvt_pk_bf16_f32 v147, v94, v95
	s_sub_i32 s101, s25, s27
	s_mov_b32 s6, s30
	s_mov_b32 s30, s27
	s_mov_b32 s27, s25
	s_mov_b32 s25, s6
	s_add_i32 s12, s12, 64
	s_add_i32 s24, s24, 2
	s_add_i32 s29, s29, 1
	s_waitcnt lgkmcnt(4)
	s_barrier
	s_cmp_lt_i32 s24, s100
	s_cbranch_scc0 .LfA_exit
	s_add_i32 s7, s29, 0xfe
	s_cmp_lt_u32 s7, s36
	s_cbranch_scc1 .LfA_iter
